# S3 entry: xor-16 butterfly level via v_permlane16_swap instead of ds_bpermute
# speedup vs baseline: 1.0011x; 1.0011x over previous
; __device__ __forceinline__ int opaque_tid() { int t = threadIdx.x; asm volatile("" : "+v"(t)); return t; }
; __device__ __forceinline__ float wave_sum(float v) {
; #pragma unroll
;     for (int o = 1; o < 64; o <<= 1) v += __shfl_xor(v, o);
;     return v;
; }
; __global__ void __launch_bounds__(NTHR) mega_fwd(Params p) {
;     ...
;             const int tid = opaque_tid(), lane = tid & 63, wave = __builtin_amdgcn_readfirstlane(tid >> 6), gw = bx * NWAVES + wave; (void)tid; (void)lane; (void)gw;
;             const float lam_init = l == 0 ? 0.2f : 0.35550906759096934f;
;             float lam; { const float* lp = p.diff_lambda + l * 256; const float sa = wave_sum(lp[lane] * lp[64 + lane]), sb = wave_sum(lp[128 + lane] * lp[192 + lane]); lam = expf(sa) - expf(sb) + lam_init; }
;             constexpr float C64 = 0.125f * 1.4426950408889634f, THR64 = att::THR / 0.125f;
;             constexpr float SC128 = 0.08838834764831845f, C128 = SC128 * 1.4426950408889634f, THR128 = att::THR / SC128;
;             const int r32 = lane & 31, hi = lane >> 5;
;             unsigned* ccnt = CTL + 32768 + l * 2048;
;             if (ON_CONV && bx >= 128) {
;                 for (int ci = 0; ci < 2; ++ci) { const int item = 2 * (bx - 128) + ci;
.LBB0_296:
	s_or_b64 exec, exec, s[0:1]
	s_xor_b64 s[0:1], s[12:13], -1
	v_writelane_b32 v255, s0, 16
	v_readlane_b32 s12, v254, 62
	v_readlane_b32 s13, v254, 63
	v_writelane_b32 v255, s1, 17
	v_readlane_b32 s0, v254, 58
	v_readlane_b32 s1, v254, 59
	s_xor_b64 s[0:1], s[0:1], -1
	v_writelane_b32 v255, s0, 18
	s_mov_b32 s5, s13
	v_mov_b32_e32 v154, v188
	v_writelane_b32 v255, s1, 19
	s_waitcnt lgkmcnt(0)
	v_readlane_b32 s14, v255, 0
	v_readlane_b32 s15, v255, 1
	v_readlane_b32 s16, v255, 2
	v_readlane_b32 s17, v255, 3
	v_readlane_b32 s18, v255, 4
	v_readlane_b32 s19, v255, 5
	v_readlane_b32 s20, v255, 6
	v_readlane_b32 s21, v255, 7
	v_readlane_b32 s22, v255, 8
	v_readlane_b32 s23, v255, 9
	v_readlane_b32 s24, v255, 10
	v_readlane_b32 s25, v255, 11
	v_readlane_b32 s26, v255, 12
	v_readlane_b32 s27, v255, 13
	v_readlane_b32 s12, v251, 17
	v_readlane_b32 s2, v255, 14
	v_readlane_b32 s13, v251, 18
	v_readlane_b32 s14, v251, 19
	v_readlane_b32 s15, v251, 20
	v_readlane_b32 s16, v251, 21
	v_readlane_b32 s17, v251, 22
	v_readlane_b32 s18, v251, 23
	v_readlane_b32 s19, v251, 24
	v_readlane_b32 s20, v251, 25
	v_readlane_b32 s21, v251, 26
	v_readlane_b32 s22, v251, 27
	v_readlane_b32 s23, v251, 28
	s_lshl_b32 s4, s2, 8
	v_readlane_b32 s24, v251, 29
	v_readlane_b32 s25, v251, 30
	v_readlane_b32 s26, v251, 31
	v_readlane_b32 s27, v251, 32
	s_mov_b64 s[12:13], s[16:17]
	s_lshl_b64 s[0:1], s[4:5], 2
	s_mov_b64 s[14:15], s[18:19]
	s_mov_b64 s[16:17], s[20:21]
	s_mov_b64 s[18:19], s[22:23]
	s_mov_b64 s[20:21], s[24:25]
	s_mov_b64 s[22:23], s[26:27]
	s_barrier
	s_add_u32 s0, s22, s0
	s_addc_u32 s1, s23, s1
	v_and_b32_e32 v0, 63, v154
	v_lshlrev_b32_e32 v0, 2, v0
	global_load_dword v2, v0, s[0:1]
	global_load_dword v3, v0, s[0:1] offset:256
	global_load_dword v4, v0, s[0:1] offset:512
	s_nop 0
	global_load_dword v0, v0, s[0:1] offset:768
	v_and_b32_e32 v5, 64, v192
	v_xor_b32_e32 v6, 1, v192
	v_add_u32_e32 v5, 64, v5
	v_cmp_lt_i32_e32 vcc, v6, v5
	v_xor_b32_e32 v7, 2, v192
	v_xor_b32_e32 v8, 4, v192
	v_cndmask_b32_e32 v6, v192, v6, vcc
	v_lshlrev_b32_e32 v162, 2, v6
	v_cmp_lt_i32_e32 vcc, v7, v5
	v_readlane_b32 s3, v255, 15
	s_lshl_b32 s4, s2, 11
	v_cndmask_b32_e32 v7, v192, v7, vcc
	v_lshlrev_b32_e32 v178, 2, v7
	v_cmp_lt_i32_e32 vcc, v8, v5
	s_mov_b32 s1, s5
	v_writelane_b32 v254, s0, 62
	v_cndmask_b32_e32 v8, v192, v8, vcc
	v_lshlrev_b32_e32 v179, 2, v8
	v_writelane_b32 v255, s2, 0
	v_writelane_b32 v255, s3, 1
	v_xor_b32_e32 v9, 8, v192
	v_writelane_b32 v255, s4, 2
	v_cmp_lt_i32_e32 vcc, v9, v5
	v_writelane_b32 v255, s5, 3
	v_writelane_b32 v255, s6, 4
	v_cndmask_b32_e32 v9, v192, v9, vcc
	v_lshlrev_b32_e32 v180, 2, v9
	v_writelane_b32 v255, s7, 5
	v_writelane_b32 v255, s8, 6
	v_writelane_b32 v255, s9, 7
	v_xor_b32_e32 v10, 16, v192
	v_writelane_b32 v255, s10, 8
	v_cmp_lt_i32_e32 vcc, v10, v5
	v_writelane_b32 v255, s11, 9
	v_writelane_b32 v255, s12, 10
	v_writelane_b32 v255, s13, 11
	v_writelane_b32 v255, s14, 12
	v_writelane_b32 v255, s15, 13
	s_lshl_b64 s[4:5], s[4:5], 2
	v_readlane_b32 s0, v252, 56
	v_xor_b32_e32 v11, 32, v192
	s_add_u32 s0, s0, s4
	v_writelane_b32 v255, s0, 20
	v_readlane_b32 s0, v252, 57
	v_writelane_b32 v255, s4, 21
	s_addc_u32 s0, s0, s5
	v_writelane_b32 v254, s1, 63
	v_writelane_b32 v255, s5, 22
	v_writelane_b32 v255, s0, 23
	s_lshl_b32 s0, s2, 9
	v_writelane_b32 v255, s0, 24
	v_readfirstlane_b32 s33, v154
	v_cmp_eq_u32_e64 s[38:39], 0, v154
	v_writelane_b32 v255, s1, 25
	v_readlane_b32 s0, v252, 58
	v_readlane_b32 s1, v252, 59
	s_waitcnt vmcnt(2)
	v_mul_f32_e32 v6, v2, v3
	s_nop 1
	v_mov_b32_dpp v6, v6 quad_perm:[1,0,3,2] row_mask:0xf bank_mask:0xf
	s_waitcnt vmcnt(0)
	v_mul_f32_e32 v12, v4, v0
	s_nop 1
	v_mov_b32_dpp v12, v12 quad_perm:[1,0,3,2] row_mask:0xf bank_mask:0xf
	s_waitcnt lgkmcnt(1)
	v_fmac_f32_e32 v6, v2, v3
	v_cndmask_b32_e32 v3, v192, v10, vcc
	s_waitcnt lgkmcnt(0)
	v_fmac_f32_e32 v12, v4, v0
	s_nop 1
	v_mov_b32_dpp v0, v6 quad_perm:[2,3,0,1] row_mask:0xf bank_mask:0xf
	s_nop 1
	v_mov_b32_dpp v2, v12 quad_perm:[2,3,0,1] row_mask:0xf bank_mask:0xf
	v_lshlrev_b32_e32 v187, 2, v3
	v_cmp_lt_i32_e32 vcc, v11, v5
	s_waitcnt lgkmcnt(1)
	v_add_f32_e32 v0, v6, v0
	s_waitcnt lgkmcnt(0)
	v_add_f32_e32 v2, v12, v2
	s_nop 1
	v_mov_b32_dpp v4, v0 row_half_mirror row_mask:0xf bank_mask:0xf
	s_nop 1
	v_mov_b32_dpp v6, v2 row_half_mirror row_mask:0xf bank_mask:0xf
	v_cndmask_b32_e32 v5, v192, v11, vcc
	v_lshlrev_b32_e32 v186, 2, v5
	s_and_b64 vcc, exec, s[0:1]
	s_waitcnt lgkmcnt(1)
	v_add_f32_e32 v0, v0, v4
	s_waitcnt lgkmcnt(0)
	v_add_f32_e32 v2, v2, v6
	s_nop 1
	v_mov_b32_dpp v4, v0 row_mirror row_mask:0xf bank_mask:0xf
	s_nop 1
	v_mov_b32_dpp v6, v2 row_mirror row_mask:0xf bank_mask:0xf
	s_waitcnt lgkmcnt(1)
	v_add_f32_e32 v0, v0, v4
	s_waitcnt lgkmcnt(0)
	v_add_f32_e32 v2, v2, v6
	v_mov_b32_e32 v3, v0
	s_nop 1
	v_permlane16_swap_b32_e32 v0, v3
	v_mov_b32_e32 v4, v2
	s_nop 1
	v_permlane16_swap_b32_e32 v2, v4
	s_waitcnt lgkmcnt(1)
	v_add_f32_e32 v0, v0, v3
	s_waitcnt lgkmcnt(0)
	v_add_f32_e32 v10, v2, v4
	ds_bpermute_b32 v11, v186, v0
	ds_bpermute_b32 v12, v186, v10
	s_cbranch_vccz .LBB0_366
	v_readlane_b32 s12, v254, 62
	v_readlane_b32 s13, v254, 63
	v_readlane_b32 s14, v255, 0
	v_readlane_b32 s15, v255, 1
	v_readlane_b32 s16, v255, 2
	v_readlane_b32 s17, v255, 3
	v_readlane_b32 s18, v255, 4
	v_readlane_b32 s19, v255, 5
	v_readlane_b32 s2, v255, 14
	s_mov_b32 s5, s13
	v_readlane_b32 s20, v255, 6
	v_readlane_b32 s21, v255, 7
	v_readlane_b32 s22, v255, 8
	v_readlane_b32 s23, v255, 9
	v_readlane_b32 s24, v255, 10
	v_readlane_b32 s25, v255, 11
	v_readlane_b32 s26, v255, 12
	v_readlane_b32 s27, v255, 13
	s_mov_b32 s1, s13
	v_readlane_b32 s3, v255, 15
	v_writelane_b32 v254, s4, 62
	s_mul_i32 s0, s2, 0x3e00
	s_lshl_b64 s[0:1], s[0:1], 2
	v_writelane_b32 v255, s6, 0
	v_writelane_b32 v255, s7, 1
	v_writelane_b32 v255, s8, 2
	v_writelane_b32 v255, s9, 3
	v_writelane_b32 v255, s10, 4
	v_writelane_b32 v255, s11, 5
	v_writelane_b32 v255, s12, 6
	v_writelane_b32 v255, s13, 7
	v_writelane_b32 v255, s14, 8
	v_writelane_b32 v255, s15, 9
	v_writelane_b32 v255, s16, 10
	v_writelane_b32 v255, s17, 11
	v_writelane_b32 v255, s18, 12
	v_writelane_b32 v255, s19, 13
	v_readlane_b32 s12, v251, 33
	v_readlane_b32 s14, v251, 35
	v_writelane_b32 v254, s5, 63
	v_readlane_b32 s15, v251, 36
	s_add_u32 s2, s14, s0
	s_addc_u32 s3, s15, s1
	v_readlane_b32 s0, v254, 60
	v_readlane_b32 s4, v255, 20
	v_readlane_b32 s1, v254, 61
	s_add_u32 s4, s4, s0
	v_readlane_b32 s0, v255, 23
	s_addc_u32 s5, s0, s1
	s_mov_b32 s0, 0
	s_mov_b64 s[6:7], -1
	v_readlane_b32 s13, v251, 34
	v_readlane_b32 s16, v251, 37
	v_readlane_b32 s17, v251, 38
	v_readlane_b32 s18, v251, 39
	v_readlane_b32 s19, v251, 40
	v_readlane_b32 s20, v251, 41
	v_readlane_b32 s21, v251, 42
	v_readlane_b32 s22, v251, 43
	v_readlane_b32 s23, v251, 44
	v_readlane_b32 s24, v251, 45
	v_readlane_b32 s25, v251, 46
	v_readlane_b32 s26, v251, 47
	v_readlane_b32 s27, v251, 48
	s_branch .LBB0_299
